# baseline (speedup 1.0000x reference)
.LBB0_848:
	s_lshl_b32 s22, s35, 8
	v_add_u32_e32 v130, s22, v208
	s_cmp_lt_i32 s34, 4
	v_and_b32_e32 v136, 0x3f8f, v130
	s_mov_b64 s[18:19], -1
	s_cbranch_scc1 .LBB0_851
	v_bfe_u32 v176, v182, 4, 1
	v_mul_u32_u24_e32 v176, 24, v176
	v_mov_b32_e32 v177, 0
	v_ashrrev_i32_e32 v131, 31, v130
	v_lshlrev_b64 v[132:133], 8, v[130:131]
	v_ashrrev_i32_e32 v131, 11, v130
	v_lshl_add_u64 v[134:135], v[194:195], 0, v[132:133]
	v_and_b32_e32 v132, -8, v131
	v_lshl_add_u32 v131, s34, 2, v209
	v_add_u32_e32 v132, v132, v131
	v_ashrrev_i32_e32 v133, 31, v132
	v_lshlrev_b64 v[138:139], 14, v[132:133]
	v_or_b32_e32 v132, v138, v136
	s_movk_i32 s2, 0x180
	v_mad_u64_u32 v[132:133], s[18:19], v132, s2, v[196:197]
	v_mad_i32_i24 v133, v139, s2, v133
	global_load_dwordx4 v[158:161], v[134:135], off
	global_load_dwordx4 v[162:165], v[134:135], off offset:16
	global_load_dwordx4 v[166:169], v[134:135], off offset:128
	global_load_dwordx4 v[170:173], v[134:135], off offset:144
	v_mov_b32_e32 v142, v126
	v_mov_b32_e32 v143, v118
	v_mov_b32_e32 v148, v128
	v_mov_b32_e32 v149, v120
	s_waitcnt vmcnt(3)
	v_pk_mul_f32 v[142:143], v[142:143], v[158:159]
	s_nop 0
	v_sub_f32_e32 v137, v142, v143
	v_mov_b32_e32 v142, v127
	v_mov_b32_e32 v143, v119
	v_pk_mul_f32 v[142:143], v[142:143], v[160:161]
	v_mul_f32_e32 v137, 0x3d93cd3a, v137
	v_sub_f32_e32 v142, v142, v143
	v_mul_f32_e32 v142, 0x3d93cd3a, v142
	v_cvt_pk_bf16_f32 v150, v137, v142
	s_waitcnt vmcnt(2)
	v_pk_mul_f32 v[148:149], v[148:149], v[162:163]
	s_nop 0
	v_sub_f32_e32 v137, v148, v149
	v_mov_b32_e32 v148, v129
	v_mov_b32_e32 v149, v121
	v_pk_mul_f32 v[148:149], v[148:149], v[164:165]
	v_mul_f32_e32 v137, 0x3d93cd3a, v137
	v_sub_f32_e32 v147, v148, v149
	v_mul_f32_e32 v147, 0x3d93cd3a, v147
	v_cvt_pk_bf16_f32 v151, v137, v147
	v_mov_b32_e32 v146, v118
	v_mov_b32_e32 v147, v126
	v_pk_mul_f32 v[138:139], v[146:147], v[158:159]
	s_nop 0
	v_add_f32_e32 v137, v138, v139
	v_mov_b32_e32 v138, v119
	v_mov_b32_e32 v139, v127
	v_pk_mul_f32 v[138:139], v[138:139], v[160:161]
	v_mov_b32_e32 v140, v120
	v_add_f32_e32 v138, v138, v139
	v_mov_b32_e32 v141, v128
	v_mul_f32_e32 v137, 0x3d93cd3a, v137
	v_mul_f32_e32 v138, 0x3d93cd3a, v138
	v_pk_mul_f32 v[140:141], v[140:141], v[162:163]
	v_cvt_pk_bf16_f32 v154, v137, v138
	v_mov_b32_e32 v142, v122
	v_add_f32_e32 v137, v140, v141
	v_mov_b32_e32 v140, v121
	v_mov_b32_e32 v141, v129
	v_pk_mul_f32 v[140:141], v[140:141], v[164:165]
	v_mul_f32_e32 v137, 0x3d93cd3a, v137
	v_add_f32_e32 v139, v140, v141
	v_mul_f32_e32 v139, 0x3d93cd3a, v139
	v_cvt_pk_bf16_f32 v155, v137, v139
	v_mov_b32_e32 v143, v114
	s_waitcnt vmcnt(1)
	v_pk_mul_f32 v[142:143], v[142:143], v[166:167]
	s_nop 0
	v_sub_f32_e32 v137, v142, v143
	v_mov_b32_e32 v142, v123
	v_mov_b32_e32 v143, v115
	v_pk_mul_f32 v[142:143], v[142:143], v[168:169]
	v_mul_f32_e32 v137, 0x3d93cd3a, v137
	v_sub_f32_e32 v142, v142, v143
	v_mul_f32_e32 v142, 0x3d93cd3a, v142
	v_cvt_pk_bf16_f32 v152, v137, v142
	v_mov_b32_e32 v134, v124
	v_mov_b32_e32 v135, v116
	s_waitcnt vmcnt(0)
	v_pk_mul_f32 v[134:135], v[134:135], v[170:171]
	s_nop 0
	v_sub_f32_e32 v134, v134, v135
	v_mul_f32_e32 v137, 0x3d93cd3a, v134
	v_mov_b32_e32 v134, v125
	v_mov_b32_e32 v135, v117
	v_pk_mul_f32 v[134:135], v[134:135], v[172:173]
	s_nop 0
	v_sub_f32_e32 v134, v134, v135
	v_mul_f32_e32 v134, 0x3d93cd3a, v134
	v_cvt_pk_bf16_f32 v153, v137, v134
	v_mov_b32_e32 v134, v114
	v_mov_b32_e32 v135, v122
	v_pk_mul_f32 v[134:135], v[134:135], v[166:167]
	v_mov_b32_e32 v138, v116
	v_add_f32_e32 v134, v134, v135
	v_mul_f32_e32 v137, 0x3d93cd3a, v134
	v_mov_b32_e32 v134, v115
	v_mov_b32_e32 v135, v123
	v_mov_b32_e32 v139, v124
	v_pk_mul_f32 v[134:135], v[134:135], v[168:169]
	v_pk_mul_f32 v[138:139], v[138:139], v[170:171]
	v_add_f32_e32 v134, v134, v135
	v_add_f32_e32 v135, v138, v139
	v_mov_b32_e32 v138, v117
	v_mov_b32_e32 v139, v125
	v_mul_f32_e32 v134, 0x3d93cd3a, v134
	v_pk_mul_f32 v[138:139], v[138:139], v[172:173]
	v_cvt_pk_bf16_f32 v156, v137, v134
	v_mul_f32_e32 v135, 0x3d93cd3a, v135
	v_add_f32_e32 v137, v138, v139
	v_lshl_add_u64 v[174:175], v[132:133], 0, v[176:177]
	s_nop 1
	v_permlane16_swap_b32_e32 v150, v152
	v_permlane16_swap_b32_e32 v151, v153
	global_store_dwordx4 v[174:175], v[150:153], off offset:256
	v_mul_f32_e32 v137, 0x3d93cd3a, v137
	v_cvt_pk_bf16_f32 v157, v135, v137
	v_lshl_add_u64 v[174:175], v[132:133], 0, v[176:177]
	s_nop 1
	v_permlane16_swap_b32_e32 v154, v156
	v_permlane16_swap_b32_e32 v155, v157
	global_store_dwordx4 v[174:175], v[154:157], off offset:320
	v_add_u32_e32 v132, s22, v210
	v_ashrrev_i32_e32 v133, 31, v132
	v_lshlrev_b64 v[134:135], 8, v[132:133]
	v_ashrrev_i32_e32 v133, 11, v132
	v_and_b32_e32 v133, -8, v133
	v_add_u32_e32 v138, v133, v131
	v_ashrrev_i32_e32 v139, 31, v138
	v_lshlrev_b64 v[138:139], 14, v[138:139]
	s_movk_i32 s18, 0x3f9f
	v_and_or_b32 v132, v132, s18, v138
	v_lshl_add_u64 v[134:135], v[194:195], 0, v[134:135]
	v_mad_u64_u32 v[132:133], s[18:19], v132, s2, v[196:197]
	v_mad_i32_i24 v133, v139, s2, v133
	global_load_dwordx4 v[158:161], v[134:135], off
	global_load_dwordx4 v[162:165], v[134:135], off offset:16
	global_load_dwordx4 v[166:169], v[134:135], off offset:128
	global_load_dwordx4 v[170:173], v[134:135], off offset:144
	v_mov_b32_e32 v142, v110
	v_mov_b32_e32 v143, v102
	v_mov_b32_e32 v148, v112
	v_mov_b32_e32 v149, v104
	s_waitcnt vmcnt(3)
	v_pk_mul_f32 v[142:143], v[142:143], v[158:159]
	s_nop 0
	v_sub_f32_e32 v137, v142, v143
	v_mov_b32_e32 v142, v111
	v_mov_b32_e32 v143, v103
	v_pk_mul_f32 v[142:143], v[142:143], v[160:161]
	v_mul_f32_e32 v137, 0x3d93cd3a, v137
	v_sub_f32_e32 v142, v142, v143
	v_mul_f32_e32 v142, 0x3d93cd3a, v142
	v_cvt_pk_bf16_f32 v150, v137, v142
	s_waitcnt vmcnt(2)
	v_pk_mul_f32 v[148:149], v[148:149], v[162:163]
	s_nop 0
	v_sub_f32_e32 v137, v148, v149
	v_mov_b32_e32 v148, v113
	v_mov_b32_e32 v149, v105
	v_pk_mul_f32 v[148:149], v[148:149], v[164:165]
	v_mul_f32_e32 v137, 0x3d93cd3a, v137
	v_sub_f32_e32 v147, v148, v149
	v_mul_f32_e32 v147, 0x3d93cd3a, v147
	v_cvt_pk_bf16_f32 v151, v137, v147
	v_mov_b32_e32 v146, v102
	v_mov_b32_e32 v147, v110
	v_pk_mul_f32 v[138:139], v[146:147], v[158:159]
	s_nop 0
	v_add_f32_e32 v137, v138, v139
	v_mov_b32_e32 v138, v103
	v_mov_b32_e32 v139, v111
	v_pk_mul_f32 v[138:139], v[138:139], v[160:161]
	v_mov_b32_e32 v140, v104
	v_add_f32_e32 v138, v138, v139
	v_mov_b32_e32 v141, v112
	v_mul_f32_e32 v137, 0x3d93cd3a, v137
	v_mul_f32_e32 v138, 0x3d93cd3a, v138
	v_pk_mul_f32 v[140:141], v[140:141], v[162:163]
	v_cvt_pk_bf16_f32 v154, v137, v138
	v_mov_b32_e32 v142, v106
	v_add_f32_e32 v137, v140, v141
	v_mov_b32_e32 v140, v105
	v_mov_b32_e32 v141, v113
	v_pk_mul_f32 v[140:141], v[140:141], v[164:165]
	v_mul_f32_e32 v137, 0x3d93cd3a, v137
	v_add_f32_e32 v139, v140, v141
	v_mul_f32_e32 v139, 0x3d93cd3a, v139
	v_cvt_pk_bf16_f32 v155, v137, v139
	v_mov_b32_e32 v143, v98
	s_waitcnt vmcnt(1)
	v_pk_mul_f32 v[142:143], v[142:143], v[166:167]
	s_nop 0
	v_sub_f32_e32 v137, v142, v143
	v_mov_b32_e32 v142, v107
	v_mov_b32_e32 v143, v99
	v_pk_mul_f32 v[142:143], v[142:143], v[168:169]
	v_mul_f32_e32 v137, 0x3d93cd3a, v137
	v_sub_f32_e32 v142, v142, v143
	v_mul_f32_e32 v142, 0x3d93cd3a, v142
	v_cvt_pk_bf16_f32 v152, v137, v142
	v_mov_b32_e32 v134, v108
	v_mov_b32_e32 v135, v100
	s_waitcnt vmcnt(0)
	v_pk_mul_f32 v[134:135], v[134:135], v[170:171]
	s_nop 0
	v_sub_f32_e32 v134, v134, v135
	v_mul_f32_e32 v137, 0x3d93cd3a, v134
	v_mov_b32_e32 v134, v109
	v_mov_b32_e32 v135, v101
	v_pk_mul_f32 v[134:135], v[134:135], v[172:173]
	s_nop 0
	v_sub_f32_e32 v134, v134, v135
	v_mul_f32_e32 v134, 0x3d93cd3a, v134
	v_cvt_pk_bf16_f32 v153, v137, v134
	v_mov_b32_e32 v134, v98
	v_mov_b32_e32 v135, v106
	v_pk_mul_f32 v[134:135], v[134:135], v[166:167]
	v_mov_b32_e32 v138, v100
	v_add_f32_e32 v134, v134, v135
	v_mul_f32_e32 v137, 0x3d93cd3a, v134
	v_mov_b32_e32 v134, v99
	v_mov_b32_e32 v135, v107
	v_mov_b32_e32 v139, v108
	v_pk_mul_f32 v[134:135], v[134:135], v[168:169]
	v_pk_mul_f32 v[138:139], v[138:139], v[170:171]
	v_add_f32_e32 v134, v134, v135
	v_add_f32_e32 v135, v138, v139
	v_mov_b32_e32 v138, v101
	v_mov_b32_e32 v139, v109
	v_mul_f32_e32 v134, 0x3d93cd3a, v134
	v_pk_mul_f32 v[138:139], v[138:139], v[172:173]
	v_cvt_pk_bf16_f32 v156, v137, v134
	v_mul_f32_e32 v135, 0x3d93cd3a, v135
	v_add_f32_e32 v137, v138, v139
	v_lshl_add_u64 v[174:175], v[132:133], 0, v[176:177]
	s_nop 1
	v_permlane16_swap_b32_e32 v150, v152
	v_permlane16_swap_b32_e32 v151, v153
	global_store_dwordx4 v[174:175], v[150:153], off offset:256
	v_mul_f32_e32 v137, 0x3d93cd3a, v137
	v_cvt_pk_bf16_f32 v157, v135, v137
	v_lshl_add_u64 v[174:175], v[132:133], 0, v[176:177]
	s_nop 1
	v_permlane16_swap_b32_e32 v154, v156
	v_permlane16_swap_b32_e32 v155, v157
	global_store_dwordx4 v[174:175], v[154:157], off offset:320
	v_add_u32_e32 v132, s22, v211
	v_ashrrev_i32_e32 v133, 31, v132
	v_lshlrev_b64 v[134:135], 8, v[132:133]
	v_ashrrev_i32_e32 v133, 11, v132
	v_and_b32_e32 v133, -8, v133
	v_add_u32_e32 v138, v133, v131
	v_ashrrev_i32_e32 v139, 31, v138
	v_lshlrev_b64 v[138:139], 14, v[138:139]
	s_movk_i32 s18, 0x3faf
	v_and_or_b32 v132, v132, s18, v138
	v_lshl_add_u64 v[134:135], v[194:195], 0, v[134:135]
	v_mad_u64_u32 v[132:133], s[18:19], v132, s2, v[196:197]
	v_mad_i32_i24 v133, v139, s2, v133
	global_load_dwordx4 v[158:161], v[134:135], off
	global_load_dwordx4 v[162:165], v[134:135], off offset:16
	global_load_dwordx4 v[166:169], v[134:135], off offset:128
	global_load_dwordx4 v[170:173], v[134:135], off offset:144
	v_mov_b32_e32 v142, v94
	v_mov_b32_e32 v143, v86
	v_mov_b32_e32 v148, v96
	v_mov_b32_e32 v149, v88
	s_waitcnt vmcnt(3)
	v_pk_mul_f32 v[142:143], v[142:143], v[158:159]
	s_nop 0
	v_sub_f32_e32 v137, v142, v143
	v_mov_b32_e32 v142, v95
	v_mov_b32_e32 v143, v87
	v_pk_mul_f32 v[142:143], v[142:143], v[160:161]
	v_mul_f32_e32 v137, 0x3d93cd3a, v137
	v_sub_f32_e32 v142, v142, v143
	v_mul_f32_e32 v142, 0x3d93cd3a, v142
	v_cvt_pk_bf16_f32 v150, v137, v142
	s_waitcnt vmcnt(2)
	v_pk_mul_f32 v[148:149], v[148:149], v[162:163]
	s_nop 0
	v_sub_f32_e32 v137, v148, v149
	v_mov_b32_e32 v148, v97
	v_mov_b32_e32 v149, v89
	v_pk_mul_f32 v[148:149], v[148:149], v[164:165]
	v_mul_f32_e32 v137, 0x3d93cd3a, v137
	v_sub_f32_e32 v147, v148, v149
	v_mul_f32_e32 v147, 0x3d93cd3a, v147
	v_cvt_pk_bf16_f32 v151, v137, v147
	v_mov_b32_e32 v146, v86
	v_mov_b32_e32 v147, v94
	v_pk_mul_f32 v[138:139], v[146:147], v[158:159]
	s_nop 0
	v_add_f32_e32 v137, v138, v139
	v_mov_b32_e32 v138, v87
	v_mov_b32_e32 v139, v95
	v_pk_mul_f32 v[138:139], v[138:139], v[160:161]
	v_mov_b32_e32 v140, v88
	v_add_f32_e32 v138, v138, v139
	v_mov_b32_e32 v141, v96
	v_mul_f32_e32 v137, 0x3d93cd3a, v137
	v_mul_f32_e32 v138, 0x3d93cd3a, v138
	v_pk_mul_f32 v[140:141], v[140:141], v[162:163]
	v_cvt_pk_bf16_f32 v154, v137, v138
	v_mov_b32_e32 v142, v90
	v_add_f32_e32 v137, v140, v141
	v_mov_b32_e32 v140, v89
	v_mov_b32_e32 v141, v97
	v_pk_mul_f32 v[140:141], v[140:141], v[164:165]
	v_mul_f32_e32 v137, 0x3d93cd3a, v137
	v_add_f32_e32 v139, v140, v141
	v_mul_f32_e32 v139, 0x3d93cd3a, v139
	v_cvt_pk_bf16_f32 v155, v137, v139
	v_mov_b32_e32 v143, v82
	s_waitcnt vmcnt(1)
	v_pk_mul_f32 v[142:143], v[142:143], v[166:167]
	s_nop 0
	v_sub_f32_e32 v137, v142, v143
	v_mov_b32_e32 v142, v91
	v_mov_b32_e32 v143, v83
	v_pk_mul_f32 v[142:143], v[142:143], v[168:169]
	v_mul_f32_e32 v137, 0x3d93cd3a, v137
	v_sub_f32_e32 v142, v142, v143
	v_mul_f32_e32 v142, 0x3d93cd3a, v142
	v_cvt_pk_bf16_f32 v152, v137, v142
	v_mov_b32_e32 v134, v92
	v_mov_b32_e32 v135, v84
	s_waitcnt vmcnt(0)
	v_pk_mul_f32 v[134:135], v[134:135], v[170:171]
	s_nop 0
	v_sub_f32_e32 v134, v134, v135
	v_mul_f32_e32 v137, 0x3d93cd3a, v134
	v_mov_b32_e32 v134, v93
	v_mov_b32_e32 v135, v85
	v_pk_mul_f32 v[134:135], v[134:135], v[172:173]
	s_nop 0
	v_sub_f32_e32 v134, v134, v135
	v_mul_f32_e32 v134, 0x3d93cd3a, v134
	v_cvt_pk_bf16_f32 v153, v137, v134
	v_mov_b32_e32 v134, v82
	v_mov_b32_e32 v135, v90
	v_pk_mul_f32 v[134:135], v[134:135], v[166:167]
	v_mov_b32_e32 v138, v84
	v_add_f32_e32 v134, v134, v135
	v_mul_f32_e32 v137, 0x3d93cd3a, v134
	v_mov_b32_e32 v134, v83
	v_mov_b32_e32 v135, v91
	v_mov_b32_e32 v139, v92
	v_pk_mul_f32 v[134:135], v[134:135], v[168:169]
	v_pk_mul_f32 v[138:139], v[138:139], v[170:171]
	v_add_f32_e32 v134, v134, v135
	v_add_f32_e32 v135, v138, v139
	v_mov_b32_e32 v138, v85
	v_mov_b32_e32 v139, v93
	v_mul_f32_e32 v134, 0x3d93cd3a, v134
	v_pk_mul_f32 v[138:139], v[138:139], v[172:173]
	v_cvt_pk_bf16_f32 v156, v137, v134
	v_mul_f32_e32 v135, 0x3d93cd3a, v135
	v_add_f32_e32 v137, v138, v139
	v_lshl_add_u64 v[174:175], v[132:133], 0, v[176:177]
	s_nop 1
	v_permlane16_swap_b32_e32 v150, v152
	v_permlane16_swap_b32_e32 v151, v153
	global_store_dwordx4 v[174:175], v[150:153], off offset:256
	v_mul_f32_e32 v137, 0x3d93cd3a, v137
	v_cvt_pk_bf16_f32 v157, v135, v137
	v_lshl_add_u64 v[174:175], v[132:133], 0, v[176:177]
	s_nop 1
	v_permlane16_swap_b32_e32 v154, v156
	v_permlane16_swap_b32_e32 v155, v157
	global_store_dwordx4 v[174:175], v[154:157], off offset:320
	v_add_u32_e32 v132, s22, v212
	v_ashrrev_i32_e32 v133, 31, v132
	v_lshlrev_b64 v[134:135], 8, v[132:133]
	v_ashrrev_i32_e32 v133, 11, v132
	v_and_b32_e32 v133, -8, v133
	v_add_u32_e32 v138, v133, v131
	v_ashrrev_i32_e32 v139, 31, v138
	v_lshlrev_b64 v[138:139], 14, v[138:139]
	s_movk_i32 s18, 0x3fbf
	v_and_or_b32 v132, v132, s18, v138
	v_lshl_add_u64 v[134:135], v[194:195], 0, v[134:135]
	v_mad_u64_u32 v[132:133], s[18:19], v132, s2, v[196:197]
	v_mad_i32_i24 v133, v139, s2, v133
	global_load_dwordx4 v[158:161], v[134:135], off
	global_load_dwordx4 v[162:165], v[134:135], off offset:16
	global_load_dwordx4 v[166:169], v[134:135], off offset:128
	global_load_dwordx4 v[170:173], v[134:135], off offset:144
	v_mov_b32_e32 v142, v78
	v_mov_b32_e32 v143, v70
	v_mov_b32_e32 v148, v80
	v_mov_b32_e32 v149, v72
	s_waitcnt vmcnt(3)
	v_pk_mul_f32 v[142:143], v[142:143], v[158:159]
	s_nop 0
	v_sub_f32_e32 v137, v142, v143
	v_mov_b32_e32 v142, v79
	v_mov_b32_e32 v143, v71
	v_pk_mul_f32 v[142:143], v[142:143], v[160:161]
	v_mul_f32_e32 v137, 0x3d93cd3a, v137
	v_sub_f32_e32 v142, v142, v143
	v_mul_f32_e32 v142, 0x3d93cd3a, v142
	v_cvt_pk_bf16_f32 v150, v137, v142
	s_waitcnt vmcnt(2)
	v_pk_mul_f32 v[148:149], v[148:149], v[162:163]
	s_nop 0
	v_sub_f32_e32 v137, v148, v149
	v_mov_b32_e32 v148, v81
	v_mov_b32_e32 v149, v73
	v_pk_mul_f32 v[148:149], v[148:149], v[164:165]
	v_mul_f32_e32 v137, 0x3d93cd3a, v137
	v_sub_f32_e32 v147, v148, v149
	v_mul_f32_e32 v147, 0x3d93cd3a, v147
	v_cvt_pk_bf16_f32 v151, v137, v147
	v_mov_b32_e32 v146, v70
	v_mov_b32_e32 v147, v78
	v_pk_mul_f32 v[138:139], v[146:147], v[158:159]
	s_nop 0
	v_add_f32_e32 v137, v138, v139
	v_mov_b32_e32 v138, v71
	v_mov_b32_e32 v139, v79
	v_pk_mul_f32 v[138:139], v[138:139], v[160:161]
	v_mov_b32_e32 v140, v72
	v_add_f32_e32 v138, v138, v139
	v_mov_b32_e32 v141, v80
	v_mul_f32_e32 v137, 0x3d93cd3a, v137
	v_mul_f32_e32 v138, 0x3d93cd3a, v138
	v_pk_mul_f32 v[140:141], v[140:141], v[162:163]
	v_cvt_pk_bf16_f32 v154, v137, v138
	v_mov_b32_e32 v142, v74
	v_add_f32_e32 v137, v140, v141
	v_mov_b32_e32 v140, v73
	v_mov_b32_e32 v141, v81
	v_pk_mul_f32 v[140:141], v[140:141], v[164:165]
	v_mul_f32_e32 v137, 0x3d93cd3a, v137
	v_add_f32_e32 v139, v140, v141
	v_mul_f32_e32 v139, 0x3d93cd3a, v139
	v_cvt_pk_bf16_f32 v155, v137, v139
	v_mov_b32_e32 v143, v66
	s_waitcnt vmcnt(1)
	v_pk_mul_f32 v[142:143], v[142:143], v[166:167]
	s_nop 0
	v_sub_f32_e32 v137, v142, v143
	v_mov_b32_e32 v142, v75
	v_mov_b32_e32 v143, v67
	v_pk_mul_f32 v[142:143], v[142:143], v[168:169]
	v_mul_f32_e32 v137, 0x3d93cd3a, v137
	v_sub_f32_e32 v142, v142, v143
	v_mul_f32_e32 v142, 0x3d93cd3a, v142
	v_cvt_pk_bf16_f32 v152, v137, v142
	v_mov_b32_e32 v134, v76
	v_mov_b32_e32 v135, v68
	s_waitcnt vmcnt(0)
	v_pk_mul_f32 v[134:135], v[134:135], v[170:171]
	s_nop 0
	v_sub_f32_e32 v134, v134, v135
	v_mul_f32_e32 v137, 0x3d93cd3a, v134
	v_mov_b32_e32 v134, v77
	v_mov_b32_e32 v135, v69
	v_pk_mul_f32 v[134:135], v[134:135], v[172:173]
	s_nop 0
	v_sub_f32_e32 v134, v134, v135
	v_mul_f32_e32 v134, 0x3d93cd3a, v134
	v_cvt_pk_bf16_f32 v153, v137, v134
	v_mov_b32_e32 v134, v66
	v_mov_b32_e32 v135, v74
	v_pk_mul_f32 v[134:135], v[134:135], v[166:167]
	v_mov_b32_e32 v138, v68
	v_add_f32_e32 v134, v134, v135
	v_mul_f32_e32 v137, 0x3d93cd3a, v134
	v_mov_b32_e32 v134, v67
	v_mov_b32_e32 v135, v75
	v_mov_b32_e32 v139, v76
	v_pk_mul_f32 v[134:135], v[134:135], v[168:169]
	v_pk_mul_f32 v[138:139], v[138:139], v[170:171]
	v_add_f32_e32 v134, v134, v135
	v_add_f32_e32 v135, v138, v139
	v_mov_b32_e32 v138, v69
	v_mov_b32_e32 v139, v77
	v_mul_f32_e32 v134, 0x3d93cd3a, v134
	v_pk_mul_f32 v[138:139], v[138:139], v[172:173]
	v_cvt_pk_bf16_f32 v156, v137, v134
	v_mul_f32_e32 v135, 0x3d93cd3a, v135
	v_add_f32_e32 v137, v138, v139
	v_lshl_add_u64 v[174:175], v[132:133], 0, v[176:177]
	s_nop 1
	v_permlane16_swap_b32_e32 v150, v152
	v_permlane16_swap_b32_e32 v151, v153
	global_store_dwordx4 v[174:175], v[150:153], off offset:256
	v_mul_f32_e32 v137, 0x3d93cd3a, v137
	v_cvt_pk_bf16_f32 v157, v135, v137
	v_lshl_add_u64 v[174:175], v[132:133], 0, v[176:177]
	s_nop 1
	v_permlane16_swap_b32_e32 v154, v156
	v_permlane16_swap_b32_e32 v155, v157
	global_store_dwordx4 v[174:175], v[154:157], off offset:320
	v_add_u32_e32 v132, s22, v213
	v_ashrrev_i32_e32 v133, 31, v132
	v_lshlrev_b64 v[134:135], 8, v[132:133]
	v_ashrrev_i32_e32 v133, 11, v132
	v_and_b32_e32 v133, -8, v133
	v_add_u32_e32 v138, v133, v131
	v_ashrrev_i32_e32 v139, 31, v138
	v_lshlrev_b64 v[138:139], 14, v[138:139]
	s_movk_i32 s18, 0x3fcf
	v_and_or_b32 v132, v132, s18, v138
	v_lshl_add_u64 v[134:135], v[194:195], 0, v[134:135]
	v_mad_u64_u32 v[132:133], s[18:19], v132, s2, v[196:197]
	v_mad_i32_i24 v133, v139, s2, v133
	global_load_dwordx4 v[158:161], v[134:135], off
	global_load_dwordx4 v[162:165], v[134:135], off offset:16
	global_load_dwordx4 v[166:169], v[134:135], off offset:128
	global_load_dwordx4 v[170:173], v[134:135], off offset:144
	v_mov_b32_e32 v142, v62
	v_mov_b32_e32 v143, v54
	v_mov_b32_e32 v148, v64
	v_mov_b32_e32 v149, v56
	s_waitcnt vmcnt(3)
	v_pk_mul_f32 v[142:143], v[142:143], v[158:159]
	s_nop 0
	v_sub_f32_e32 v137, v142, v143
	v_mov_b32_e32 v142, v63
	v_mov_b32_e32 v143, v55
	v_pk_mul_f32 v[142:143], v[142:143], v[160:161]
	v_mul_f32_e32 v137, 0x3d93cd3a, v137
	v_sub_f32_e32 v142, v142, v143
	v_mul_f32_e32 v142, 0x3d93cd3a, v142
	v_cvt_pk_bf16_f32 v150, v137, v142
	s_waitcnt vmcnt(2)
	v_pk_mul_f32 v[148:149], v[148:149], v[162:163]
	s_nop 0
	v_sub_f32_e32 v137, v148, v149
	v_mov_b32_e32 v148, v65
	v_mov_b32_e32 v149, v57
	v_pk_mul_f32 v[148:149], v[148:149], v[164:165]
	v_mul_f32_e32 v137, 0x3d93cd3a, v137
	v_sub_f32_e32 v147, v148, v149
	v_mul_f32_e32 v147, 0x3d93cd3a, v147
	v_cvt_pk_bf16_f32 v151, v137, v147
	v_mov_b32_e32 v146, v54
	v_mov_b32_e32 v147, v62
	v_pk_mul_f32 v[138:139], v[146:147], v[158:159]
	s_nop 0
	v_add_f32_e32 v137, v138, v139
	v_mov_b32_e32 v138, v55
	v_mov_b32_e32 v139, v63
	v_pk_mul_f32 v[138:139], v[138:139], v[160:161]
	v_mov_b32_e32 v140, v56
	v_add_f32_e32 v138, v138, v139
	v_mov_b32_e32 v141, v64
	v_mul_f32_e32 v137, 0x3d93cd3a, v137
	v_mul_f32_e32 v138, 0x3d93cd3a, v138
	v_pk_mul_f32 v[140:141], v[140:141], v[162:163]
	v_cvt_pk_bf16_f32 v154, v137, v138
	v_mov_b32_e32 v142, v58
	v_add_f32_e32 v137, v140, v141
	v_mov_b32_e32 v140, v57
	v_mov_b32_e32 v141, v65
	v_pk_mul_f32 v[140:141], v[140:141], v[164:165]
	v_mul_f32_e32 v137, 0x3d93cd3a, v137
	v_add_f32_e32 v139, v140, v141
	v_mul_f32_e32 v139, 0x3d93cd3a, v139
	v_cvt_pk_bf16_f32 v155, v137, v139
	v_mov_b32_e32 v143, v50
	s_waitcnt vmcnt(1)
	v_pk_mul_f32 v[142:143], v[142:143], v[166:167]
	s_nop 0
	v_sub_f32_e32 v137, v142, v143
	v_mov_b32_e32 v142, v59
	v_mov_b32_e32 v143, v51
	v_pk_mul_f32 v[142:143], v[142:143], v[168:169]
	v_mul_f32_e32 v137, 0x3d93cd3a, v137
	v_sub_f32_e32 v142, v142, v143
	v_mul_f32_e32 v142, 0x3d93cd3a, v142
	v_cvt_pk_bf16_f32 v152, v137, v142
	v_mov_b32_e32 v134, v60
	v_mov_b32_e32 v135, v52
	s_waitcnt vmcnt(0)
	v_pk_mul_f32 v[134:135], v[134:135], v[170:171]
	s_nop 0
	v_sub_f32_e32 v134, v134, v135
	v_mul_f32_e32 v137, 0x3d93cd3a, v134
	v_mov_b32_e32 v134, v61
	v_mov_b32_e32 v135, v53
	v_pk_mul_f32 v[134:135], v[134:135], v[172:173]
	s_nop 0
	v_sub_f32_e32 v134, v134, v135
	v_mul_f32_e32 v134, 0x3d93cd3a, v134
	v_cvt_pk_bf16_f32 v153, v137, v134
	v_mov_b32_e32 v134, v50
	v_mov_b32_e32 v135, v58
	v_pk_mul_f32 v[134:135], v[134:135], v[166:167]
	v_mov_b32_e32 v138, v52
	v_add_f32_e32 v134, v134, v135
	v_mul_f32_e32 v137, 0x3d93cd3a, v134
	v_mov_b32_e32 v134, v51
	v_mov_b32_e32 v135, v59
	v_mov_b32_e32 v139, v60
	v_pk_mul_f32 v[134:135], v[134:135], v[168:169]
	v_pk_mul_f32 v[138:139], v[138:139], v[170:171]
	v_add_f32_e32 v134, v134, v135
	v_add_f32_e32 v135, v138, v139
	v_mov_b32_e32 v138, v53
	v_mov_b32_e32 v139, v61
	v_mul_f32_e32 v134, 0x3d93cd3a, v134
	v_pk_mul_f32 v[138:139], v[138:139], v[172:173]
	v_cvt_pk_bf16_f32 v156, v137, v134
	v_mul_f32_e32 v135, 0x3d93cd3a, v135
	v_add_f32_e32 v137, v138, v139
	v_lshl_add_u64 v[174:175], v[132:133], 0, v[176:177]
	s_nop 1
	v_permlane16_swap_b32_e32 v150, v152
	v_permlane16_swap_b32_e32 v151, v153
	global_store_dwordx4 v[174:175], v[150:153], off offset:256
	v_mul_f32_e32 v137, 0x3d93cd3a, v137
	v_cvt_pk_bf16_f32 v157, v135, v137
	v_lshl_add_u64 v[174:175], v[132:133], 0, v[176:177]
	s_nop 1
	v_permlane16_swap_b32_e32 v154, v156
	v_permlane16_swap_b32_e32 v155, v157
	global_store_dwordx4 v[174:175], v[154:157], off offset:320
	v_add_u32_e32 v132, s22, v214
	v_ashrrev_i32_e32 v133, 31, v132
	v_lshlrev_b64 v[134:135], 8, v[132:133]
	v_ashrrev_i32_e32 v133, 11, v132
	v_and_b32_e32 v133, -8, v133
	v_add_u32_e32 v138, v133, v131
	v_ashrrev_i32_e32 v139, 31, v138
	v_lshlrev_b64 v[138:139], 14, v[138:139]
	s_movk_i32 s18, 0x3fdf
	v_and_or_b32 v132, v132, s18, v138
	v_lshl_add_u64 v[134:135], v[194:195], 0, v[134:135]
	v_mad_u64_u32 v[132:133], s[18:19], v132, s2, v[196:197]
	v_mad_i32_i24 v133, v139, s2, v133
	global_load_dwordx4 v[158:161], v[134:135], off
	global_load_dwordx4 v[162:165], v[134:135], off offset:16
	global_load_dwordx4 v[166:169], v[134:135], off offset:128
	global_load_dwordx4 v[170:173], v[134:135], off offset:144
	v_mov_b32_e32 v142, v46
	v_mov_b32_e32 v143, v38
	v_mov_b32_e32 v148, v48
	v_mov_b32_e32 v149, v40
	s_waitcnt vmcnt(3)
	v_pk_mul_f32 v[142:143], v[142:143], v[158:159]
	s_nop 0
	v_sub_f32_e32 v137, v142, v143
	v_mov_b32_e32 v142, v47
	v_mov_b32_e32 v143, v39
	v_pk_mul_f32 v[142:143], v[142:143], v[160:161]
	v_mul_f32_e32 v137, 0x3d93cd3a, v137
	v_sub_f32_e32 v142, v142, v143
	v_mul_f32_e32 v142, 0x3d93cd3a, v142
	v_cvt_pk_bf16_f32 v150, v137, v142
	s_waitcnt vmcnt(2)
	v_pk_mul_f32 v[148:149], v[148:149], v[162:163]
	s_nop 0
	v_sub_f32_e32 v137, v148, v149
	v_mov_b32_e32 v148, v49
	v_mov_b32_e32 v149, v41
	v_pk_mul_f32 v[148:149], v[148:149], v[164:165]
	v_mul_f32_e32 v137, 0x3d93cd3a, v137
	v_sub_f32_e32 v147, v148, v149
	v_mul_f32_e32 v147, 0x3d93cd3a, v147
	v_cvt_pk_bf16_f32 v151, v137, v147
	v_mov_b32_e32 v146, v38
	v_mov_b32_e32 v147, v46
	v_pk_mul_f32 v[138:139], v[146:147], v[158:159]
	s_nop 0
	v_add_f32_e32 v137, v138, v139
	v_mov_b32_e32 v138, v39
	v_mov_b32_e32 v139, v47
	v_pk_mul_f32 v[138:139], v[138:139], v[160:161]
	v_mov_b32_e32 v140, v40
	v_add_f32_e32 v138, v138, v139
	v_mov_b32_e32 v141, v48
	v_mul_f32_e32 v137, 0x3d93cd3a, v137
	v_mul_f32_e32 v138, 0x3d93cd3a, v138
	v_pk_mul_f32 v[140:141], v[140:141], v[162:163]
	v_cvt_pk_bf16_f32 v154, v137, v138
	v_mov_b32_e32 v142, v42
	v_add_f32_e32 v137, v140, v141
	v_mov_b32_e32 v140, v41
	v_mov_b32_e32 v141, v49
	v_pk_mul_f32 v[140:141], v[140:141], v[164:165]
	v_mul_f32_e32 v137, 0x3d93cd3a, v137
	v_add_f32_e32 v139, v140, v141
	v_mul_f32_e32 v139, 0x3d93cd3a, v139
	v_cvt_pk_bf16_f32 v155, v137, v139
	v_mov_b32_e32 v143, v34
	s_waitcnt vmcnt(1)
	v_pk_mul_f32 v[142:143], v[142:143], v[166:167]
	s_nop 0
	v_sub_f32_e32 v137, v142, v143
	v_mov_b32_e32 v142, v43
	v_mov_b32_e32 v143, v35
	v_pk_mul_f32 v[142:143], v[142:143], v[168:169]
	v_mul_f32_e32 v137, 0x3d93cd3a, v137
	v_sub_f32_e32 v142, v142, v143
	v_mul_f32_e32 v142, 0x3d93cd3a, v142
	v_cvt_pk_bf16_f32 v152, v137, v142
	v_mov_b32_e32 v134, v44
	v_mov_b32_e32 v135, v36
	s_waitcnt vmcnt(0)
	v_pk_mul_f32 v[134:135], v[134:135], v[170:171]
	s_nop 0
	v_sub_f32_e32 v134, v134, v135
	v_mul_f32_e32 v137, 0x3d93cd3a, v134
	v_mov_b32_e32 v134, v45
	v_mov_b32_e32 v135, v37
	v_pk_mul_f32 v[134:135], v[134:135], v[172:173]
	s_nop 0
	v_sub_f32_e32 v134, v134, v135
	v_mul_f32_e32 v134, 0x3d93cd3a, v134
	v_cvt_pk_bf16_f32 v153, v137, v134
	v_mov_b32_e32 v134, v34
	v_mov_b32_e32 v135, v42
	v_pk_mul_f32 v[134:135], v[134:135], v[166:167]
	v_mov_b32_e32 v138, v36
	v_add_f32_e32 v134, v134, v135
	v_mul_f32_e32 v137, 0x3d93cd3a, v134
	v_mov_b32_e32 v134, v35
	v_mov_b32_e32 v135, v43
	v_mov_b32_e32 v139, v44
	v_pk_mul_f32 v[134:135], v[134:135], v[168:169]
	v_pk_mul_f32 v[138:139], v[138:139], v[170:171]
	v_add_f32_e32 v134, v134, v135
	v_add_f32_e32 v135, v138, v139
	v_mov_b32_e32 v138, v37
	v_mov_b32_e32 v139, v45
	v_mul_f32_e32 v134, 0x3d93cd3a, v134
	v_pk_mul_f32 v[138:139], v[138:139], v[172:173]
	v_cvt_pk_bf16_f32 v156, v137, v134
	v_mul_f32_e32 v135, 0x3d93cd3a, v135
	v_add_f32_e32 v137, v138, v139
	v_lshl_add_u64 v[174:175], v[132:133], 0, v[176:177]
	s_nop 1
	v_permlane16_swap_b32_e32 v150, v152
	v_permlane16_swap_b32_e32 v151, v153
	global_store_dwordx4 v[174:175], v[150:153], off offset:256
	v_mul_f32_e32 v137, 0x3d93cd3a, v137
	v_cvt_pk_bf16_f32 v157, v135, v137
	v_lshl_add_u64 v[174:175], v[132:133], 0, v[176:177]
	s_nop 1
	v_permlane16_swap_b32_e32 v154, v156
	v_permlane16_swap_b32_e32 v155, v157
	global_store_dwordx4 v[174:175], v[154:157], off offset:320
	v_add_u32_e32 v132, s22, v215
	v_ashrrev_i32_e32 v133, 31, v132
	v_lshlrev_b64 v[134:135], 8, v[132:133]
	v_ashrrev_i32_e32 v133, 11, v132
	v_and_b32_e32 v133, -8, v133
	v_add_u32_e32 v138, v133, v131
	v_ashrrev_i32_e32 v139, 31, v138
	v_lshlrev_b64 v[138:139], 14, v[138:139]
	s_movk_i32 s18, 0x3fef
	v_and_or_b32 v132, v132, s18, v138
	v_lshl_add_u64 v[134:135], v[194:195], 0, v[134:135]
	v_mad_u64_u32 v[132:133], s[18:19], v132, s2, v[196:197]
	v_mad_i32_i24 v133, v139, s2, v133
	global_load_dwordx4 v[158:161], v[134:135], off
	global_load_dwordx4 v[162:165], v[134:135], off offset:16
	global_load_dwordx4 v[166:169], v[134:135], off offset:128
	global_load_dwordx4 v[170:173], v[134:135], off offset:144
	v_mov_b32_e32 v142, v30
	v_mov_b32_e32 v143, v22
	v_mov_b32_e32 v148, v32
	v_mov_b32_e32 v149, v24
	s_waitcnt vmcnt(3)
	v_pk_mul_f32 v[142:143], v[142:143], v[158:159]
	s_nop 0
	v_sub_f32_e32 v137, v142, v143
	v_mov_b32_e32 v142, v31
	v_mov_b32_e32 v143, v23
	v_pk_mul_f32 v[142:143], v[142:143], v[160:161]
	v_mul_f32_e32 v137, 0x3d93cd3a, v137
	v_sub_f32_e32 v142, v142, v143
	v_mul_f32_e32 v142, 0x3d93cd3a, v142
	v_cvt_pk_bf16_f32 v150, v137, v142
	s_waitcnt vmcnt(2)
	v_pk_mul_f32 v[148:149], v[148:149], v[162:163]
	s_nop 0
	v_sub_f32_e32 v137, v148, v149
	v_mov_b32_e32 v148, v33
	v_mov_b32_e32 v149, v25
	v_pk_mul_f32 v[148:149], v[148:149], v[164:165]
	v_mul_f32_e32 v137, 0x3d93cd3a, v137
	v_sub_f32_e32 v147, v148, v149
	v_mul_f32_e32 v147, 0x3d93cd3a, v147
	v_cvt_pk_bf16_f32 v151, v137, v147
	v_mov_b32_e32 v146, v22
	v_mov_b32_e32 v147, v30
	v_pk_mul_f32 v[138:139], v[146:147], v[158:159]
	s_nop 0
	v_add_f32_e32 v137, v138, v139
	v_mov_b32_e32 v138, v23
	v_mov_b32_e32 v139, v31
	v_pk_mul_f32 v[138:139], v[138:139], v[160:161]
	v_mov_b32_e32 v140, v24
	v_add_f32_e32 v138, v138, v139
	v_mov_b32_e32 v141, v32
	v_mul_f32_e32 v137, 0x3d93cd3a, v137
	v_mul_f32_e32 v138, 0x3d93cd3a, v138
	v_pk_mul_f32 v[140:141], v[140:141], v[162:163]
	v_cvt_pk_bf16_f32 v154, v137, v138
	v_mov_b32_e32 v142, v26
	v_add_f32_e32 v137, v140, v141
	v_mov_b32_e32 v140, v25
	v_mov_b32_e32 v141, v33
	v_pk_mul_f32 v[140:141], v[140:141], v[164:165]
	v_mul_f32_e32 v137, 0x3d93cd3a, v137
	v_add_f32_e32 v139, v140, v141
	v_mul_f32_e32 v139, 0x3d93cd3a, v139
	v_cvt_pk_bf16_f32 v155, v137, v139
	v_mov_b32_e32 v143, v18
	s_waitcnt vmcnt(1)
	v_pk_mul_f32 v[142:143], v[142:143], v[166:167]
	s_nop 0
	v_sub_f32_e32 v137, v142, v143
	v_mov_b32_e32 v142, v27
	v_mov_b32_e32 v143, v19
	v_pk_mul_f32 v[142:143], v[142:143], v[168:169]
	v_mul_f32_e32 v137, 0x3d93cd3a, v137
	v_sub_f32_e32 v142, v142, v143
	v_mul_f32_e32 v142, 0x3d93cd3a, v142
	v_cvt_pk_bf16_f32 v152, v137, v142
	v_mov_b32_e32 v134, v28
	v_mov_b32_e32 v135, v20
	s_waitcnt vmcnt(0)
	v_pk_mul_f32 v[134:135], v[134:135], v[170:171]
	s_nop 0
	v_sub_f32_e32 v134, v134, v135
	v_mul_f32_e32 v137, 0x3d93cd3a, v134
	v_mov_b32_e32 v134, v29
	v_mov_b32_e32 v135, v21
	v_pk_mul_f32 v[134:135], v[134:135], v[172:173]
	s_nop 0
	v_sub_f32_e32 v134, v134, v135
	v_mul_f32_e32 v134, 0x3d93cd3a, v134
	v_cvt_pk_bf16_f32 v153, v137, v134
	v_mov_b32_e32 v134, v18
	v_mov_b32_e32 v135, v26
	v_pk_mul_f32 v[134:135], v[134:135], v[166:167]
	v_mov_b32_e32 v138, v20
	v_add_f32_e32 v134, v134, v135
	v_mul_f32_e32 v137, 0x3d93cd3a, v134
	v_mov_b32_e32 v134, v19
	v_mov_b32_e32 v135, v27
	v_mov_b32_e32 v139, v28
	v_pk_mul_f32 v[134:135], v[134:135], v[168:169]
	v_pk_mul_f32 v[138:139], v[138:139], v[170:171]
	v_add_f32_e32 v134, v134, v135
	v_add_f32_e32 v135, v138, v139
	v_mov_b32_e32 v138, v21
	v_mov_b32_e32 v139, v29
	v_mul_f32_e32 v134, 0x3d93cd3a, v134
	v_pk_mul_f32 v[138:139], v[138:139], v[172:173]
	v_cvt_pk_bf16_f32 v156, v137, v134
	v_mul_f32_e32 v135, 0x3d93cd3a, v135
	v_add_f32_e32 v137, v138, v139
	v_lshl_add_u64 v[174:175], v[132:133], 0, v[176:177]
	s_nop 1
	v_permlane16_swap_b32_e32 v150, v152
	v_permlane16_swap_b32_e32 v151, v153
	global_store_dwordx4 v[174:175], v[150:153], off offset:256
	v_mul_f32_e32 v137, 0x3d93cd3a, v137
	v_cvt_pk_bf16_f32 v157, v135, v137
	v_lshl_add_u64 v[174:175], v[132:133], 0, v[176:177]
	s_nop 1
	v_permlane16_swap_b32_e32 v154, v156
	v_permlane16_swap_b32_e32 v155, v157
	global_store_dwordx4 v[174:175], v[154:157], off offset:320
	v_add_u32_e32 v132, s22, v216
	v_ashrrev_i32_e32 v133, 31, v132
	v_lshlrev_b64 v[134:135], 8, v[132:133]
	v_ashrrev_i32_e32 v133, 11, v132
	v_and_b32_e32 v133, -8, v133
	v_add_u32_e32 v138, v133, v131
	v_ashrrev_i32_e32 v139, 31, v138
	v_lshlrev_b64 v[138:139], 14, v[138:139]
	s_movk_i32 s18, 0x3fff
	v_and_or_b32 v131, v132, s18, v138
	v_lshl_add_u64 v[134:135], v[194:195], 0, v[134:135]
	v_mad_u64_u32 v[132:133], s[18:19], v131, s2, v[196:197]
	v_mad_i32_i24 v133, v139, s2, v133
	global_load_dwordx4 v[158:161], v[134:135], off
	global_load_dwordx4 v[162:165], v[134:135], off offset:16
	global_load_dwordx4 v[166:169], v[134:135], off offset:128
	global_load_dwordx4 v[170:173], v[134:135], off offset:144
	v_mov_b32_e32 v142, v14
	v_mov_b32_e32 v143, v6
	v_mov_b32_e32 v148, v16
	v_mov_b32_e32 v149, v8
	s_waitcnt vmcnt(3)
	v_pk_mul_f32 v[142:143], v[142:143], v[158:159]
	s_nop 0
	v_sub_f32_e32 v131, v142, v143
	v_mov_b32_e32 v142, v15
	v_mov_b32_e32 v143, v7
	v_pk_mul_f32 v[142:143], v[142:143], v[160:161]
	v_mul_f32_e32 v131, 0x3d93cd3a, v131
	v_sub_f32_e32 v137, v142, v143
	v_mul_f32_e32 v137, 0x3d93cd3a, v137
	v_cvt_pk_bf16_f32 v150, v131, v137
	s_waitcnt vmcnt(2)
	v_pk_mul_f32 v[148:149], v[148:149], v[162:163]
	s_nop 0
	v_sub_f32_e32 v131, v148, v149
	v_mov_b32_e32 v148, v17
	v_mov_b32_e32 v149, v9
	v_pk_mul_f32 v[148:149], v[148:149], v[164:165]
	v_mul_f32_e32 v131, 0x3d93cd3a, v131
	v_sub_f32_e32 v137, v148, v149
	v_mul_f32_e32 v137, 0x3d93cd3a, v137
	v_cvt_pk_bf16_f32 v151, v131, v137
	v_mov_b32_e32 v146, v6
	v_mov_b32_e32 v147, v14
	v_pk_mul_f32 v[138:139], v[146:147], v[158:159]
	s_nop 0
	v_add_f32_e32 v131, v138, v139
	v_mov_b32_e32 v138, v7
	v_mov_b32_e32 v139, v15
	v_pk_mul_f32 v[138:139], v[138:139], v[160:161]
	v_mov_b32_e32 v140, v8
	v_mov_b32_e32 v141, v16
	v_mul_f32_e32 v131, 0x3d93cd3a, v131
	v_add_f32_e32 v137, v138, v139
	v_pk_mul_f32 v[140:141], v[140:141], v[162:163]
	v_mul_f32_e32 v137, 0x3d93cd3a, v137
	v_cvt_pk_bf16_f32 v154, v131, v137
	v_add_f32_e32 v131, v140, v141
	v_mov_b32_e32 v140, v9
	v_mov_b32_e32 v141, v17
	v_pk_mul_f32 v[140:141], v[140:141], v[164:165]
	v_mul_f32_e32 v131, 0x3d93cd3a, v131
	v_add_f32_e32 v137, v140, v141
	v_mul_f32_e32 v137, 0x3d93cd3a, v137
	v_cvt_pk_bf16_f32 v155, v131, v137
	v_mov_b32_e32 v142, v10
	v_mov_b32_e32 v143, v2
	s_waitcnt vmcnt(1)
	v_pk_mul_f32 v[142:143], v[142:143], v[166:167]
	s_nop 0
	v_sub_f32_e32 v131, v142, v143
	v_mov_b32_e32 v142, v11
	v_mov_b32_e32 v143, v3
	v_pk_mul_f32 v[142:143], v[142:143], v[168:169]
	v_mul_f32_e32 v131, 0x3d93cd3a, v131
	v_sub_f32_e32 v137, v142, v143
	v_mov_b32_e32 v134, v12
	v_mov_b32_e32 v135, v4
	v_mul_f32_e32 v137, 0x3d93cd3a, v137
	v_cvt_pk_bf16_f32 v152, v131, v137
	s_waitcnt vmcnt(0)
	v_pk_mul_f32 v[134:135], v[134:135], v[170:171]
	s_nop 0
	v_sub_f32_e32 v131, v134, v135
	v_mov_b32_e32 v134, v13
	v_mov_b32_e32 v135, v5
	v_pk_mul_f32 v[134:135], v[134:135], v[172:173]
	v_mul_f32_e32 v131, 0x3d93cd3a, v131
	v_sub_f32_e32 v134, v134, v135
	v_mul_f32_e32 v134, 0x3d93cd3a, v134
	v_cvt_pk_bf16_f32 v153, v131, v134
	v_mov_b32_e32 v134, v2
	v_mov_b32_e32 v135, v10
	v_pk_mul_f32 v[134:135], v[134:135], v[166:167]
	v_mov_b32_e32 v138, v4
	v_add_f32_e32 v131, v134, v135
	v_mov_b32_e32 v134, v3
	v_mov_b32_e32 v135, v11
	v_pk_mul_f32 v[134:135], v[134:135], v[168:169]
	v_mov_b32_e32 v139, v12
	v_add_f32_e32 v134, v134, v135
	v_mul_f32_e32 v131, 0x3d93cd3a, v131
	v_mul_f32_e32 v134, 0x3d93cd3a, v134
	v_pk_mul_f32 v[138:139], v[138:139], v[170:171]
	v_cvt_pk_bf16_f32 v156, v131, v134
	v_lshl_add_u64 v[174:175], v[132:133], 0, v[176:177]
	s_nop 1
	v_permlane16_swap_b32_e32 v150, v152
	v_permlane16_swap_b32_e32 v151, v153
	global_store_dwordx4 v[174:175], v[150:153], off offset:256
	v_add_f32_e32 v131, v138, v139
	v_mov_b32_e32 v138, v5
	v_mov_b32_e32 v139, v13
	v_pk_mul_f32 v[138:139], v[138:139], v[172:173]
	v_mul_f32_e32 v131, 0x3d93cd3a, v131
	v_add_f32_e32 v135, v138, v139
	v_mul_f32_e32 v135, 0x3d93cd3a, v135
	v_cvt_pk_bf16_f32 v157, v131, v135
	v_lshl_add_u64 v[174:175], v[132:133], 0, v[176:177]
	s_nop 1
	v_permlane16_swap_b32_e32 v154, v156
	v_permlane16_swap_b32_e32 v155, v157
	global_store_dwordx4 v[174:175], v[154:157], off offset:320
	s_cbranch_execz .LBB0_852
